# v052 plus: rare-path branches inverted so the common path executes one branch per tile, and one unneeded s_nop before the permlane swap block removed
# baseline (speedup 1.0000x reference)
; __device__ __forceinline__ void finishSM(f32x16& p0, f32x16& p1, float alpha, float& l_reg, bf16x8& pa0, bf16x8& pa1, bf16x8& pa2, bf16x8& pa3) {
; #pragma unroll
;   for (int r = 0; r < 16; ++r) p1[r] = __builtin_amdgcn_exp2f(p1[r]);
;   float ps = 0;
; #pragma unroll
;   for (int r = 0; r < 16; ++r) ps += p0[r];
; #pragma unroll
;   for (int r = 0; r < 16; ++r) ps += p1[r];
;   { auto rr = __builtin_amdgcn_permlane32_swap(__float_as_uint(ps), __float_as_uint(ps), false, false);
;     ps = __uint_as_float(rr[0]) + __uint_as_float(rr[1]); }
;   l_reg = l_reg * alpha + ps;
;     ...
;   PK4(p0, 0, pa0); PK4(p0, 8, pa1); PK4(p1, 0, pa2); PK4(p1, 8, pa3);
;     ...
; }
; template <int NQ> __device__ __forceinline__ void qkt(f32x16& p0, f32x16& p1, const char* Ks, const bf16x8* qr, int r32, int hi, int kcolB) {
;   p0 = f32x16{}; p1 = f32x16{};
; #pragma unroll
;   for (int d0 = 0; d0 < NQ; ++d0) { const int cb = kcolB + (d0 * 16 + hi * 8) * 2;
;     bf16x8 b0 = *reinterpret_cast<const bf16x8*>(Ks + KSWZ(r32, cb));
;     bf16x8 b1 = *reinterpret_cast<const bf16x8*>(Ks + KSWZ(32 + r32, cb));
;     p0 = __builtin_amdgcn_mfma_f32_32x32x16_bf16(b0, qr[d0], p0, 0, 0, 0);
;     p1 = __builtin_amdgcn_mfma_f32_32x32x16_bf16(b1, qr[d0], p1, 0, 0, 0); }
; }
; __device__ __forceinline__ void qkt0(f32x16& p0, f32x16& p1, const char* Ks, const char* Qs, int r32, int hi, int kcolB, const f32x16& init) {
; #pragma unroll
;   for (int d0 = 0; d0 < 4; ++d0) { const int cb = kcolB + (d0 * 16 + hi * 8) * 2;
;     bf16x8 b0 = *reinterpret_cast<const bf16x8*>(Ks + KSWZ(r32, cb));
;     bf16x8 b1 = *reinterpret_cast<const bf16x8*>(Ks + KSWZ(32 + r32, cb));
;     bf16x8 qf = *reinterpret_cast<const bf16x8*>(Qs + r32 * 128 + (((2 * d0 + hi) ^ (r32 & 7)) << 4));
;     if (d0 == 0) { p0 = __builtin_amdgcn_mfma_f32_32x32x16_bf16(b0, qf, init, 0, 0, 0); p1 = __builtin_amdgcn_mfma_f32_32x32x16_bf16(b1, qf, init, 0, 0, 0); }
;     else { p0 = __builtin_amdgcn_mfma_f32_32x32x16_bf16(b0, qf, p0, 0, 0, 0); p1 = __builtin_amdgcn_mfma_f32_32x32x16_bf16(b1, qf, p1, 0, 0, 0); } }
; }
.Lstag_a:
	s_add_i32 s34, s59, 0
	v_add_u32_e32 v112, s34, v193
	v_add_u32_e32 v116, s34, v194
	ds_read_b128 v[112:115], v112 offset:16384
	ds_read_b128 v[202:205], v181
	ds_read_b128 v[206:209], v180
	ds_read_b128 v[210:213], v116 offset:16384
	v_exp_f32_e32 v234, v96
	v_add_f32_e32 v96, 0, v161
	s_waitcnt lgkmcnt(2)
	v_mfma_f32_32x32x16_bf16 v[128:143], v[112:115], v[202:205], v[80:95]
	v_add_u32_e32 v112, s34, v197
	v_add_u32_e32 v113, s34, v195
	v_add_f32_e32 v96, v163, v96
	ds_read_b128 v[214:217], v112 offset:16384
	ds_read_b128 v[218:221], v113 offset:16384
	v_add_f32_e32 v96, v159, v96
	v_add_f32_e32 v96, v162, v96
	v_add_f32_e32 v96, v157, v96
	s_waitcnt lgkmcnt(2)
	v_mfma_f32_32x32x16_bf16 v[112:127], v[210:213], v[202:205], v[80:95]
	v_add_f32_e32 v96, v160, v96
	v_add_f32_e32 v96, v156, v96
	v_add_f32_e32 v96, v158, v96
	v_add_f32_e32 v96, v153, v96
	v_add_f32_e32 v96, v155, v96
	v_add_f32_e32 v96, v151, v96
	v_add_f32_e32 v96, v154, v96
	s_waitcnt lgkmcnt(0)
	v_mfma_f32_32x32x16_bf16 v[128:143], v[218:221], v[206:209], v[128:143]
	v_add_f32_e32 v96, v149, v96
	v_add_u32_e32 v201, s34, v199
	v_add_u32_e32 v210, s34, v196
	v_exp_f32_e32 v235, v97
	v_add_f32_e32 v96, v152, v96
	ds_read_b128 v[202:205], v201 offset:16384
	ds_read_b128 v[210:213], v210 offset:16384
	ds_read_b128 v[222:225], v179
	ds_read_b128 v[226:229], v178
	v_exp_f32_e32 v236, v98
	v_mfma_f32_32x32x16_bf16 v[112:127], v[214:217], v[206:209], v[112:127]
	v_add_f32_e32 v96, v148, v96
	v_exp_f32_e32 v237, v99
	v_add_f32_e32 v96, v150, v96
	v_exp_f32_e32 v238, v100
	v_add_f32_e32 v96, v234, v96
	v_exp_f32_e32 v239, v101
	v_add_f32_e32 v96, v235, v96
	v_exp_f32_e32 v206, v102
	s_waitcnt lgkmcnt(1)
	v_mfma_f32_32x32x16_bf16 v[128:143], v[210:213], v[222:225], v[128:143]
	v_add_f32_e32 v96, v236, v96
	v_exp_f32_e32 v207, v103
	v_add_f32_e32 v96, v237, v96
	v_add_u32_e32 v201, s34, v200
	v_add_u32_e32 v230, s34, v198
	v_exp_f32_e32 v208, v104
	v_add_f32_e32 v96, v238, v96
	v_mfma_f32_32x32x16_bf16 v[112:127], v[202:205], v[222:225], v[112:127]
	ds_read_b128 v[218:221], v201 offset:16384
	ds_read_b128 v[230:233], v230 offset:16384
	v_exp_f32_e32 v209, v105
	v_add_f32_e32 v96, v239, v96
	v_exp_f32_e32 v214, v106
	v_add_f32_e32 v96, v206, v96
	v_exp_f32_e32 v215, v107
	v_add_f32_e32 v96, v207, v96
	v_exp_f32_e32 v216, v108
	v_add_f32_e32 v96, v208, v96
	v_exp_f32_e32 v210, v109
	v_add_f32_e32 v96, v209, v96
	v_exp_f32_e32 v211, v110
	s_waitcnt lgkmcnt(0)
	v_mfma_f32_32x32x16_bf16 v[128:143], v[230:233], v[226:229], v[128:143]
	v_add_f32_e32 v96, v214, v96
	v_exp_f32_e32 v111, v111
	v_add_f32_e32 v96, v215, v96
	v_add_f32_e32 v96, v216, v96
	v_add_f32_e32 v96, v210, v96
	v_add_f32_e32 v96, v211, v96
	v_add_f32_e32 v201, v111, v96
	v_mfma_f32_32x32x16_bf16 v[112:127], v[218:221], v[226:229], v[112:127]
	v_mov_b32_e32 v202, v201
	s_nop 1
	v_permlane32_swap_b32_e32 v201, v202
	v_cvt_pk_bf16_f32 v96, v161, v163
	v_cvt_pk_bf16_f32 v97, v159, v162
	v_cvt_pk_bf16_f32 v98, v157, v160
	v_cvt_pk_bf16_f32 v99, v156, v158
	v_cvt_pk_bf16_f32 v100, v153, v155
	v_cvt_pk_bf16_f32 v101, v151, v154
	v_cvt_pk_bf16_f32 v102, v149, v152
	v_cvt_pk_bf16_f32 v103, v148, v150
	v_cvt_pk_bf16_f32 v104, v234, v235
	v_cvt_pk_bf16_f32 v105, v236, v237
	v_cvt_pk_bf16_f32 v106, v238, v239
	v_cvt_pk_bf16_f32 v107, v206, v207
	v_cvt_pk_bf16_f32 v108, v208, v209
	v_cvt_pk_bf16_f32 v109, v214, v215
	v_cvt_pk_bf16_f32 v110, v216, v210
	v_cvt_pk_bf16_f32 v111, v211, v111
	v_permlane32_swap_b32_e32 v96, v98
	v_permlane32_swap_b32_e32 v97, v99
	v_permlane32_swap_b32_e32 v100, v102
	v_permlane32_swap_b32_e32 v101, v103
	v_permlane32_swap_b32_e32 v104, v106
	v_permlane32_swap_b32_e32 v105, v107
	v_permlane32_swap_b32_e32 v108, v110
	v_permlane32_swap_b32_e32 v109, v111
	v_add_u32_e32 v203, s36, v175
	ds_read_b64_tr_b16 v[148:149], v203 offset:0
	ds_read_b64_tr_b16 v[150:151], v203 offset:0x800
	ds_read_b64_tr_b16 v[152:153], v203 offset:0x1000
	ds_read_b64_tr_b16 v[154:155], v203 offset:0x1800
	ds_read_b64_tr_b16 v[156:157], v203 offset:0x2000
	ds_read_b64_tr_b16 v[158:159], v203 offset:0x2800
	ds_read_b64_tr_b16 v[160:161], v203 offset:0x3000
	ds_read_b64_tr_b16 v[162:163], v203 offset:0x3800
	s_add_i32 s34, s58, 1
	s_waitcnt lgkmcnt(0)
; __device__ __forceinline__ void pv_d0(f32x16* o, int vb, bf16x8 pa0, bf16x8 pa1, bf16x8 pa2, bf16x8 pa3) {
;   s16x4 la[4], ha[4];
;   rd8<0>(la, ha, vb); WAITDEP(0, la, ha); mma4(o[0], la, ha, pa0, pa1, pa2, pa3);
;   rd8<1>(la, ha, vb); WAITDEP(0, la, ha); mma4(o[1], la, ha, pa0, pa1, pa2, pa3);
;   rd8<2>(la, ha, vb); WAITDEP(0, la, ha); mma4(o[2], la, ha, pa0, pa1, pa2, pa3);
;   rd8<3>(la, ha, vb); WAITDEP(0, la, ha); mma4(o[3], la, ha, pa0, pa1, pa2, pa3);
; }
; template <int MODE>
; __device__ __forceinline__ void attn_unit(bf16r* P0, const bf16r* __restrict__ PKV, int rowbase, int seqL, int h, int blk, float lam,
;                                           const float* __restrict__ subg, const float* __restrict__ tsrc, char* lds) {
;   constexpr int NQ = (MODE == 0) ? 4 : 8;
;   int tid_ = threadIdx.x; asm volatile("" : "+v"(tid_));
;   const int tid = tid_, wid = __builtin_amdgcn_readfirstlane(tid >> 6), lane = tid & 63, r32 = lane & 31, hi = lane >> 5;
;   float* ws = (float*)(lds + OFF_WS) + wid * 64; float* li_l = ws; float* al_l = ws + 32;
;   float* tb = (float*)(lds + OFF_TB);
;   int qrow, kcolB, tbase, NT, colbase, gr = 0, rs = 0, qc = 0, cmap = 0;
;   float bL = 0.f, bR = 0.f;
;   if constexpr (MODE == 0) {
;     cmap = wid >> 2; qrow = blk * 128 + (wid & 3) * 32; kcolB = cmap * 128; tbase = 0; NT = seqL / KVBLK; colbase = h * 128;
;     bL = tsrc[15 * 8 + h] * LOG2E; bR = tsrc[31 * 8 + h] * LOG2E;
;     { const int rel = tid - 256, n = rel < 0 ? -rel : rel;
;       int bk = n < 8 ? n : min(15, 8 + (31 - __clz((n * n) >> 6))); if (rel > 0) bk += 16;
;       tb[tid] = tsrc[bk * 8 + h] * LOG2E; }
;   } else {
;     const int rows = seqL / 64; qrow = blk * 256 + wid * 32; kcolB = 0; colbase = 1024 + h * 128; NT = 12;
;     const int rs0 = min(max(blk * 4 - 4, 0), rows - 8); tbase = min(rs0, rows - 12);
;     gr = blk * 4 + (wid >> 1); rs = min(max(gr - 4, 0), rows - 8); qc = (wid & 1) * 32 + r32;
;     for (int i = tid; i < 15 * 128; i += 512) { const int dr = i >> 7, dc = (i & 127) - 48; tb[i] = (dc >= 0 && dc < 31) ? tsrc[(h * 15 + dr) * 31 + dc] * LOG2E : 0.f; }
;   }
;   const bf16r* Qw = P0 + (size_t)(rowbase + qrow + r32) * LD + colbase + (MODE == 0 ? cmap * 64 : 0) + hi * 8;
;   const bf16r* Kh = PKV + (size_t)rowbase * LD + h * 128; const bf16r* Vh = Kh + 1024;
;   float m_reg = -1e30f, l_reg = 0; f32x16 o[4] = {};
	s_add_i32 s60, s37, 0
	v_mfma_f32_32x32x16_bf16 v[64:79], v[96:99], v[148:151], v[64:79]
	ds_read_b64_tr_b16 v[148:149], v203 offset:0x200
	ds_read_b64_tr_b16 v[150:151], v203 offset:0xa00
	ds_read_b64_tr_b16 v[204:205], v203 offset:0x1200
	ds_read_b64_tr_b16 v[206:207], v203 offset:0x1a00
	ds_read_b64_tr_b16 v[208:209], v203 offset:0x2200
	ds_read_b64_tr_b16 v[210:211], v203 offset:0x2a00
	ds_read_b64_tr_b16 v[212:213], v203 offset:0x3200
	v_mfma_f32_32x32x16_bf16 v[64:79], v[100:103], v[152:155], v[64:79]
	ds_read_b64_tr_b16 v[214:215], v203 offset:0x3a00
	s_min_i32 s34, s34, s39
	s_waitcnt lgkmcnt(0)
	s_cmp_ge_i32 s34, s56
	s_cselect_b32 s35, s57, 0
	s_add_i32 s35, s35, s34
	s_lshl_b32 s34, s35, 6
	v_mfma_f32_32x32x16_bf16 v[64:79], v[104:107], v[156:159], v[64:79]
	v_mfma_f32_32x32x16_bf16 v[48:63], v[96:99], v[148:151], v[48:63]
	ds_read_b64_tr_b16 v[148:149], v203 offset:0x400
	ds_read_b64_tr_b16 v[150:151], v203 offset:0xc00
	ds_read_b64_tr_b16 v[152:153], v203 offset:0x1400
	ds_read_b64_tr_b16 v[154:155], v203 offset:0x1c00
	v_mfma_f32_32x32x16_bf16 v[64:79], v[108:111], v[160:163], v[64:79]
	ds_read_b64_tr_b16 v[160:161], v203 offset:0x2400
	ds_read_b64_tr_b16 v[162:163], v203 offset:0x2c00
	v_mfma_f32_32x32x16_bf16 v[48:63], v[100:103], v[204:207], v[48:63]
	ds_read_b64_tr_b16 v[204:205], v203 offset:0x3400
	ds_read_b64_tr_b16 v[206:207], v203 offset:0x3c00
	s_nop 0
	s_waitcnt lgkmcnt(0)
	ds_read_b64_tr_b16 v[216:217], v203 offset:0x600
	ds_read_b64_tr_b16 v[218:219], v203 offset:0xe00
	s_nop 0
	v_mfma_f32_32x32x16_bf16 v[32:47], v[96:99], v[148:151], v[32:47]
	s_lshl_b32 s98, s34, 12
	s_add_u32 s98, s30, s98
	s_addc_u32 s99, s31, 0
	v_mfma_f32_32x32x16_bf16 v[48:63], v[104:107], v[208:211], v[48:63]
	ds_read_b64_tr_b16 v[208:209], v203 offset:0x1600
	ds_read_b64_tr_b16 v[210:211], v203 offset:0x1e00
	ds_read_b64_tr_b16 v[220:221], v203 offset:0x2600
	ds_read_b64_tr_b16 v[222:223], v203 offset:0x2e00
	ds_read_b64_tr_b16 v[224:225], v203 offset:0x3600
	ds_read_b64_tr_b16 v[226:227], v203 offset:0x3e00
	v_mfma_f32_32x32x16_bf16 v[32:47], v[100:103], v[152:155], v[32:47]
	s_waitcnt lgkmcnt(0)
	s_waitcnt vmcnt(0)
	global_load_dwordx4 v[156:159], v252, s[98:99] offset:2048
	s_nop 0
	global_load_dwordx4 v[148:151], v252, s[98:99]
	v_add_u32_e32 v203, s60, v183
	v_mfma_f32_32x32x16_bf16 v[32:47], v[104:107], v[160:163], v[32:47]
	global_load_dwordx4 v[160:163], v253, s[98:99] offset:2048
	s_nop 0
	global_load_dwordx4 v[152:155], v253, s[98:99]
	ds_write_b128 v203, v[6:9]
	v_add_u32_e32 v6, s60, v189
	ds_write_b128 v6, v[144:147]
	v_add_u32_e32 v6, s60, v190
	ds_write_b128 v6, v[2:5] offset:16384
	v_add_u32_e32 v2, s60, v191
	v_mfma_f32_32x32x16_bf16 v[16:31], v[96:99], v[216:219], v[16:31]
	ds_write_b128 v2, v[10:13] offset:16384
	v_max_f32_e32 v2, v128, v129
	v_max3_f32 v2, v2, v130, v131
	v_max3_f32 v2, v2, v132, v133
	v_max3_f32 v2, v2, v134, v135
	v_mfma_f32_32x32x16_bf16 v[16:31], v[100:103], v[208:211], v[16:31]
	v_max3_f32 v2, v2, v136, v137
	v_max3_f32 v2, v2, v138, v139
	v_max3_f32 v2, v2, v140, v141
	v_max3_f32 v2, v2, v142, v143
	v_max3_f32 v2, v2, v112, v113
	v_max3_f32 v2, v2, v114, v115
	v_max3_f32 v2, v2, v116, v117
	v_mfma_f32_32x32x16_bf16 v[16:31], v[104:107], v[220:223], v[16:31]
	v_max3_f32 v2, v2, v118, v119
	v_max3_f32 v2, v2, v120, v121
	v_max3_f32 v2, v2, v122, v123
	v_max3_f32 v2, v2, v124, v125
	v_max3_f32 v2, v2, v126, v127
	v_mov_b32_e32 v3, v2
	s_nop 1
	v_permlane32_swap_b32_e32 v2, v3
	v_mfma_f32_32x32x16_bf16 v[48:63], v[108:111], v[212:215], v[48:63]
	v_max_f32_e32 v2, v2, v3
	v_cmp_ge_f32_e32 vcc, s49, v2
	s_cmp_eq_u64 vcc, exec
	v_mov_b32_e32 v203, 1.0
	v_mfma_f32_32x32x16_bf16 v[32:47], v[108:111], v[204:207], v[32:47]
	v_mfma_f32_32x32x16_bf16 v[16:31], v[108:111], v[224:227], v[16:31]
	s_cbranch_scc1 .LBB0_220
	s_branch .LBB0_229

; __device__ __forceinline__ void finishSM(f32x16& p0, f32x16& p1, float alpha, float& l_reg, bf16x8& pa0, bf16x8& pa1, bf16x8& pa2, bf16x8& pa3) {
; #pragma unroll
;   for (int r = 0; r < 16; ++r) p1[r] = __builtin_amdgcn_exp2f(p1[r]);
;   float ps = 0;
; #pragma unroll
;   for (int r = 0; r < 16; ++r) ps += p0[r];
; #pragma unroll
;   for (int r = 0; r < 16; ++r) ps += p1[r];
;   { auto rr = __builtin_amdgcn_permlane32_swap(__float_as_uint(ps), __float_as_uint(ps), false, false);
;     ps = __uint_as_float(rr[0]) + __uint_as_float(rr[1]); }
;   l_reg = l_reg * alpha + ps;
;     ...
;   PK4(p0, 0, pa0); PK4(p0, 8, pa1); PK4(p1, 0, pa2); PK4(p1, 8, pa3);
;     ...
; }
; template <int NQ> __device__ __forceinline__ void qkt(f32x16& p0, f32x16& p1, const char* Ks, const bf16x8* qr, int r32, int hi, int kcolB) {
;   p0 = f32x16{}; p1 = f32x16{};
; #pragma unroll
;   for (int d0 = 0; d0 < NQ; ++d0) { const int cb = kcolB + (d0 * 16 + hi * 8) * 2;
;     bf16x8 b0 = *reinterpret_cast<const bf16x8*>(Ks + KSWZ(r32, cb));
;     bf16x8 b1 = *reinterpret_cast<const bf16x8*>(Ks + KSWZ(32 + r32, cb));
;     p0 = __builtin_amdgcn_mfma_f32_32x32x16_bf16(b0, qr[d0], p0, 0, 0, 0);
;     p1 = __builtin_amdgcn_mfma_f32_32x32x16_bf16(b1, qr[d0], p1, 0, 0, 0); }
; }
; __device__ __forceinline__ void qkt0(f32x16& p0, f32x16& p1, const char* Ks, const char* Qs, int r32, int hi, int kcolB, const f32x16& init) {
; #pragma unroll
;   for (int d0 = 0; d0 < 4; ++d0) { const int cb = kcolB + (d0 * 16 + hi * 8) * 2;
;     bf16x8 b0 = *reinterpret_cast<const bf16x8*>(Ks + KSWZ(r32, cb));
;     bf16x8 b1 = *reinterpret_cast<const bf16x8*>(Ks + KSWZ(32 + r32, cb));
;     bf16x8 qf = *reinterpret_cast<const bf16x8*>(Qs + r32 * 128 + (((2 * d0 + hi) ^ (r32 & 7)) << 4));
;     if (d0 == 0) { p0 = __builtin_amdgcn_mfma_f32_32x32x16_bf16(b0, qf, init, 0, 0, 0); p1 = __builtin_amdgcn_mfma_f32_32x32x16_bf16(b1, qf, init, 0, 0, 0); }
;     else { p0 = __builtin_amdgcn_mfma_f32_32x32x16_bf16(b0, qf, p0, 0, 0, 0); p1 = __builtin_amdgcn_mfma_f32_32x32x16_bf16(b1, qf, p1, 0, 0, 0); } }
; }
.Lstag_b:
	v_exp_f32_e32 v224, v128
	v_exp_f32_e32 v225, v129
	v_exp_f32_e32 v226, v130
	v_exp_f32_e32 v227, v131
	v_exp_f32_e32 v228, v132
	v_exp_f32_e32 v229, v133
	v_exp_f32_e32 v230, v134
	v_exp_f32_e32 v231, v135
	v_exp_f32_e32 v232, v136
	v_exp_f32_e32 v233, v137
	v_exp_f32_e32 v234, v138
	v_exp_f32_e32 v235, v139
	v_exp_f32_e32 v236, v140
	v_exp_f32_e32 v237, v141
	v_exp_f32_e32 v238, v142
	v_exp_f32_e32 v239, v143
	v_add_u32_e32 v2, s60, v193
	ds_read_b128 v[2:5], v2 offset:16384
	ds_read_b128 v[6:9], v181
	v_add_u32_e32 v96, s60, v194
	ds_read_b128 v[10:13], v180
	v_add_u32_e32 v97, s60, v195
	v_add_u32_e32 v208, s60, v199
	s_waitcnt lgkmcnt(1)
	v_mfma_f32_32x32x16_bf16 v[128:143], v[2:5], v[6:9], v[80:95]
	ds_read_b128 v[2:5], v96 offset:16384
	v_add_u32_e32 v96, s60, v197
	ds_read_b128 v[144:147], v96 offset:16384
	ds_read_b128 v[204:207], v97 offset:16384
	v_add_u32_e32 v209, s60, v196
	v_exp_f32_e32 v240, v114
	v_exp_f32_e32 v241, v115
	v_exp_f32_e32 v242, v116
	s_waitcnt lgkmcnt(0)
	v_mfma_f32_32x32x16_bf16 v[128:143], v[204:207], v[10:13], v[128:143]
	v_exp_f32_e32 v206, v112
	v_exp_f32_e32 v207, v113
	v_exp_f32_e32 v243, v117
	v_exp_f32_e32 v244, v118
	v_add_u32_e32 v216, s60, v200
	v_add_u32_e32 v220, s60, v198
	v_mfma_f32_32x32x16_bf16 v[96:111], v[2:5], v[6:9], v[80:95]
	ds_read_b128 v[2:5], v208 offset:16384
	ds_read_b128 v[6:9], v209 offset:16384
	ds_read_b128 v[208:211], v179
	ds_read_b128 v[212:215], v178
	ds_read_b128 v[216:219], v216 offset:16384
	ds_read_b128 v[220:223], v220 offset:16384
	v_cvt_pk_bf16_f32 v116, v224, v225
	v_cvt_pk_bf16_f32 v117, v226, v227
	v_cvt_pk_bf16_f32 v118, v228, v229
	s_nop 0
	v_permlane32_swap_b32_e32 v116, v118
	v_mfma_f32_32x32x16_bf16 v[96:111], v[144:147], v[10:13], v[96:111]
	v_exp_f32_e32 v10, v119
	v_exp_f32_e32 v11, v120
	v_exp_f32_e32 v12, v121
	v_exp_f32_e32 v13, v122
	v_exp_f32_e32 v144, v123
	v_exp_f32_e32 v145, v124
	v_exp_f32_e32 v146, v125
	s_waitcnt lgkmcnt(3)
	v_mfma_f32_32x32x16_bf16 v[128:143], v[6:9], v[208:211], v[128:143]
	v_add_f32_e32 v8, 0, v224
	v_add_f32_e32 v8, v225, v8
	v_add_f32_e32 v8, v226, v8
	v_add_f32_e32 v8, v227, v8
	v_add_f32_e32 v8, v228, v8
	v_exp_f32_e32 v6, v126
	v_exp_f32_e32 v7, v127
	v_mfma_f32_32x32x16_bf16 v[96:111], v[2:5], v[208:211], v[96:111]
	v_add_f32_e32 v2, v229, v8
	v_add_f32_e32 v2, v230, v2
	v_add_f32_e32 v2, v231, v2
	v_add_f32_e32 v2, v232, v2
	v_add_f32_e32 v2, v233, v2
	v_add_f32_e32 v2, v234, v2
	v_add_f32_e32 v2, v235, v2
	v_add_f32_e32 v2, v236, v2
	v_add_f32_e32 v2, v237, v2
	v_add_f32_e32 v2, v238, v2
	v_add_f32_e32 v2, v239, v2
	v_add_f32_e32 v2, v206, v2
	v_add_f32_e32 v2, v207, v2
	v_add_f32_e32 v2, v240, v2
	v_add_f32_e32 v2, v241, v2
	v_add_f32_e32 v2, v242, v2
	v_add_f32_e32 v2, v243, v2
	v_add_f32_e32 v2, v244, v2
	v_add_f32_e32 v2, v10, v2
	v_add_f32_e32 v2, v11, v2
	v_add_f32_e32 v2, v12, v2
	s_waitcnt lgkmcnt(0)
	v_mfma_f32_32x32x16_bf16 v[128:143], v[220:223], v[212:215], v[128:143]
	v_add_f32_e32 v2, v13, v2
	v_add_f32_e32 v2, v144, v2
	v_add_f32_e32 v2, v145, v2
	v_add_f32_e32 v2, v146, v2
	v_add_f32_e32 v2, v6, v2
	v_add_f32_e32 v204, v7, v2
	v_mov_b32_e32 v205, v204
	v_mfma_f32_32x32x16_bf16 v[96:111], v[216:219], v[212:215], v[96:111]
	v_cvt_pk_bf16_f32 v119, v230, v231
	v_cvt_pk_bf16_f32 v112, v232, v233
	v_cvt_pk_bf16_f32 v113, v234, v235
	v_cvt_pk_bf16_f32 v114, v236, v237
	v_cvt_pk_bf16_f32 v115, v238, v239
	s_nop 0
	v_permlane32_swap_b32_e32 v204, v205
	v_permlane32_swap_b32_e32 v112, v114
	v_permlane32_swap_b32_e32 v113, v115
	v_cvt_pk_bf16_f32 v120, v206, v207
	v_cvt_pk_bf16_f32 v121, v240, v241
	v_cvt_pk_bf16_f32 v122, v242, v243
	v_cvt_pk_bf16_f32 v123, v244, v10
	v_cvt_pk_bf16_f32 v124, v11, v12
	v_cvt_pk_bf16_f32 v125, v13, v144
	v_cvt_pk_bf16_f32 v126, v145, v146
	v_cvt_pk_bf16_f32 v127, v6, v7
	v_permlane32_swap_b32_e32 v117, v119
	v_permlane32_swap_b32_e32 v120, v122
	v_permlane32_swap_b32_e32 v121, v123
	v_permlane32_swap_b32_e32 v124, v126
	v_permlane32_swap_b32_e32 v125, v127
	v_add_u32_e32 v230, s59, v175
	ds_read_b64_tr_b16 v[2:3], v230 offset:0
	ds_read_b64_tr_b16 v[4:5], v230 offset:0x800
	ds_read_b64_tr_b16 v[6:7], v230 offset:0x1000
	ds_read_b64_tr_b16 v[8:9], v230 offset:0x1800
	ds_read_b64_tr_b16 v[10:11], v230 offset:0x2000
	ds_read_b64_tr_b16 v[12:13], v230 offset:0x2800
	ds_read_b64_tr_b16 v[144:145], v230 offset:0x3000
	ds_read_b64_tr_b16 v[146:147], v230 offset:0x3800
	s_add_i32 s58, s58, 2
	s_waitcnt lgkmcnt(0)
; __device__ __forceinline__ void pv_d0(f32x16* o, int vb, bf16x8 pa0, bf16x8 pa1, bf16x8 pa2, bf16x8 pa3) {
;   s16x4 la[4], ha[4];
;   rd8<0>(la, ha, vb); WAITDEP(0, la, ha); mma4(o[0], la, ha, pa0, pa1, pa2, pa3);
;   rd8<1>(la, ha, vb); WAITDEP(0, la, ha); mma4(o[1], la, ha, pa0, pa1, pa2, pa3);
;   rd8<2>(la, ha, vb); WAITDEP(0, la, ha); mma4(o[2], la, ha, pa0, pa1, pa2, pa3);
;   rd8<3>(la, ha, vb); WAITDEP(0, la, ha); mma4(o[3], la, ha, pa0, pa1, pa2, pa3);
; }
; template <int MODE>
; __device__ __forceinline__ void attn_unit(bf16r* P0, const bf16r* __restrict__ PKV, int rowbase, int seqL, int h, int blk, float lam,
;                                           const float* __restrict__ subg, const float* __restrict__ tsrc, char* lds) {
;   constexpr int NQ = (MODE == 0) ? 4 : 8;
;   int tid_ = threadIdx.x; asm volatile("" : "+v"(tid_));
;   const int tid = tid_, wid = __builtin_amdgcn_readfirstlane(tid >> 6), lane = tid & 63, r32 = lane & 31, hi = lane >> 5;
;   float* ws = (float*)(lds + OFF_WS) + wid * 64; float* li_l = ws; float* al_l = ws + 32;
;   float* tb = (float*)(lds + OFF_TB);
;   int qrow, kcolB, tbase, NT, colbase, gr = 0, rs = 0, qc = 0, cmap = 0;
;   float bL = 0.f, bR = 0.f;
;   if constexpr (MODE == 0) {
;     cmap = wid >> 2; qrow = blk * 128 + (wid & 3) * 32; kcolB = cmap * 128; tbase = 0; NT = seqL / KVBLK; colbase = h * 128;
;     bL = tsrc[15 * 8 + h] * LOG2E; bR = tsrc[31 * 8 + h] * LOG2E;
;     { const int rel = tid - 256, n = rel < 0 ? -rel : rel;
;       int bk = n < 8 ? n : min(15, 8 + (31 - __clz((n * n) >> 6))); if (rel > 0) bk += 16;
;       tb[tid] = tsrc[bk * 8 + h] * LOG2E; }
;   } else {
;     const int rows = seqL / 64; qrow = blk * 256 + wid * 32; kcolB = 0; colbase = 1024 + h * 128; NT = 12;
;     const int rs0 = min(max(blk * 4 - 4, 0), rows - 8); tbase = min(rs0, rows - 12);
;     gr = blk * 4 + (wid >> 1); rs = min(max(gr - 4, 0), rows - 8); qc = (wid & 1) * 32 + r32;
;     for (int i = tid; i < 15 * 128; i += 512) { const int dr = i >> 7, dc = (i & 127) - 48; tb[i] = (dc >= 0 && dc < 31) ? tsrc[(h * 15 + dr) * 31 + dc] * LOG2E : 0.f; }
;   }
;   const bf16r* Qw = P0 + (size_t)(rowbase + qrow + r32) * LD + colbase + (MODE == 0 ? cmap * 64 : 0) + hi * 8;
;   const bf16r* Kh = PKV + (size_t)rowbase * LD + h * 128; const bf16r* Vh = Kh + 1024;
;   float m_reg = -1e30f, l_reg = 0; f32x16 o[4] = {};
	s_add_i32 s34, s36, 0
	v_mfma_f32_32x32x16_bf16 v[64:79], v[116:119], v[2:5], v[64:79]
	ds_read_b64_tr_b16 v[2:3], v230 offset:0x200
	ds_read_b64_tr_b16 v[4:5], v230 offset:0xa00
	ds_read_b64_tr_b16 v[206:207], v230 offset:0x1200
	ds_read_b64_tr_b16 v[208:209], v230 offset:0x1a00
	ds_read_b64_tr_b16 v[210:211], v230 offset:0x2200
	ds_read_b64_tr_b16 v[212:213], v230 offset:0x2a00
	ds_read_b64_tr_b16 v[214:215], v230 offset:0x3200
	v_mfma_f32_32x32x16_bf16 v[64:79], v[112:115], v[6:9], v[64:79]
	ds_read_b64_tr_b16 v[216:217], v230 offset:0x3a00
	s_min_i32 s35, s58, s39
	s_waitcnt lgkmcnt(0)
	s_cmp_ge_i32 s35, s56
	s_cselect_b32 s60, s57, 0
	s_add_i32 s60, s60, s35
	s_lshl_b32 s35, s60, 6
	v_mfma_f32_32x32x16_bf16 v[48:63], v[116:119], v[2:5], v[48:63]
	ds_read_b64_tr_b16 v[2:3], v230 offset:0x400
	ds_read_b64_tr_b16 v[4:5], v230 offset:0xc00
	ds_read_b64_tr_b16 v[6:7], v230 offset:0x1400
	ds_read_b64_tr_b16 v[8:9], v230 offset:0x1c00
	v_mfma_f32_32x32x16_bf16 v[64:79], v[120:123], v[10:13], v[64:79]
	ds_read_b64_tr_b16 v[10:11], v230 offset:0x2400
	ds_read_b64_tr_b16 v[12:13], v230 offset:0x2c00
	v_mfma_f32_32x32x16_bf16 v[48:63], v[112:115], v[206:209], v[48:63]
	ds_read_b64_tr_b16 v[206:207], v230 offset:0x3400
	ds_read_b64_tr_b16 v[208:209], v230 offset:0x3c00
	s_nop 0
	s_waitcnt lgkmcnt(0)
	ds_read_b64_tr_b16 v[218:219], v230 offset:0x600
	ds_read_b64_tr_b16 v[220:221], v230 offset:0xe00
	s_nop 0
	v_mfma_f32_32x32x16_bf16 v[32:47], v[116:119], v[2:5], v[32:47]
	s_lshl_b32 s98, s35, 12
	s_add_u32 s98, s30, s98
	s_addc_u32 s99, s31, 0
	v_mfma_f32_32x32x16_bf16 v[48:63], v[120:123], v[210:213], v[48:63]
	ds_read_b64_tr_b16 v[210:211], v230 offset:0x1600
	ds_read_b64_tr_b16 v[212:213], v230 offset:0x1e00
	ds_read_b64_tr_b16 v[222:223], v230 offset:0x2600
	ds_read_b64_tr_b16 v[224:225], v230 offset:0x2e00
	ds_read_b64_tr_b16 v[226:227], v230 offset:0x3600
	ds_read_b64_tr_b16 v[228:229], v230 offset:0x3e00
	v_mfma_f32_32x32x16_bf16 v[32:47], v[112:115], v[6:9], v[32:47]
	s_waitcnt lgkmcnt(0)
	s_waitcnt vmcnt(0)
	v_mfma_f32_32x32x16_bf16 v[48:63], v[124:127], v[214:217], v[48:63]
	global_load_dwordx4 v[6:9], v252, s[98:99] offset:2048
	s_nop 0
	global_load_dwordx4 v[2:5], v252, s[98:99]
	v_mfma_f32_32x32x16_bf16 v[64:79], v[124:127], v[144:147], v[64:79]
	v_mfma_f32_32x32x16_bf16 v[32:47], v[120:123], v[10:13], v[32:47]
	global_load_dwordx4 v[144:147], v253, s[98:99] offset:2048
	global_load_dwordx4 v[10:13], v253, s[98:99]
	v_add_u32_e32 v214, s34, v183
	ds_write_b128 v214, v[156:159]
	v_add_u32_e32 v156, s34, v189
	ds_write_b128 v156, v[160:163]
	v_add_u32_e32 v156, s34, v190
	ds_write_b128 v156, v[148:151] offset:16384
	v_mfma_f32_32x32x16_bf16 v[16:31], v[116:119], v[218:221], v[16:31]
	v_add_u32_e32 v148, s34, v191
	ds_write_b128 v148, v[152:155] offset:16384
	v_max_f32_e32 v148, v128, v129
	v_max3_f32 v148, v148, v130, v131
	v_max3_f32 v148, v148, v132, v133
	v_mfma_f32_32x32x16_bf16 v[16:31], v[112:115], v[210:213], v[16:31]
	v_max3_f32 v116, v148, v134, v135
	v_max3_f32 v116, v116, v136, v137
	v_max3_f32 v116, v116, v138, v139
	v_max3_f32 v116, v116, v140, v141
	v_max3_f32 v116, v116, v142, v143
	v_max3_f32 v116, v116, v96, v97
	v_max3_f32 v116, v116, v98, v99
	v_mfma_f32_32x32x16_bf16 v[16:31], v[120:123], v[222:225], v[16:31]
	v_max3_f32 v112, v116, v100, v101
	v_max3_f32 v112, v112, v102, v103
	v_max3_f32 v112, v112, v104, v105
	v_max3_f32 v112, v112, v106, v107
	v_max3_f32 v112, v112, v108, v109
	v_max3_f32 v112, v112, v110, v111
	v_mov_b32_e32 v113, v112
	v_mfma_f32_32x32x16_bf16 v[32:47], v[124:127], v[206:209], v[32:47]
	s_nop 0
	v_permlane32_swap_b32_e32 v112, v113
	v_max_f32_e32 v113, v112, v113
	v_cmp_ge_f32_e32 vcc, s49, v113
	s_cmp_eq_u64 vcc, exec
	v_mfma_f32_32x32x16_bf16 v[16:31], v[124:127], v[226:229], v[16:31]
	v_mov_b32_e32 v112, 1.0
	s_cbranch_scc1 .LBB0_227
	s_branch .LBB0_230

; #define SBAR() __builtin_amdgcn_sched_barrier(0)
; __device__ __forceinline__ int crow(int r, int hi) { return (r & 3) + 8 * (r >> 2) + 4 * hi; }
; #define RESC(a) do { if (__any((a) < 1.f)) { if (hi == 0) al_l[r32] = (a); asm volatile("s_waitcnt lgkmcnt(0)" ::: "memory"); \
;     _Pragma("unroll") for (int d = 0; d < 4; ++d) _Pragma("unroll") for (int r = 0; r < 16; ++r) o[d][r] *= al_l[crow(r, hi)]; } } while (0)
; #define NEGM(i) do { const float nv_ = CB(i) - m_reg; if (__any(nv_ != negm[0])) { _Pragma("unroll") for (int r = 0; r < 16; ++r) negm[r] = nv_; asm volatile("" : "+v"(negm)); } } while (0)
; template <int MODE>
; __device__ __forceinline__ void attn_unit(bf16r* P0, const bf16r* __restrict__ PKV, int rowbase, int seqL, int h, int blk, float lam,
;                                           const float* __restrict__ subg, const float* __restrict__ tsrc, char* lds) {
;     ...
;     NEGM(NH - 1); SBAR(); qkt0(pB0, pB1, lds + sCur + SLOT_K, Qs, r32, hi, kcolB, negm);
;     finishSM(pA0, pA1, alA, l_reg, pa0, pa1, pa2, pa3); SBAR();
;     pv_d0(o, vb0 + sPrev, pa0, pa1, pa2, pa3); scoreConst(pB0, pB1, m_reg, alB); SBAR();
;     RESC(alB);
;     finishSM(pB0, pB1, alB, l_reg, pa0, pa1, pa2, pa3); SBAR();
;     pv_d0(o, vb0 + sCur, pa0, pa1, pa2, pa3);
;     ...
;   if (hi == 0) li_l[r32] = l_reg; asm volatile("s_waitcnt lgkmcnt(0)" ::: "memory");
;   float rli[16];
; #pragma unroll
;   for (int r = 0; r < 16; ++r) rli[r] = __builtin_amdgcn_rcpf(li_l[crow(r, hi)]);
.LBB0_240:
	v_exp_f32_e32 v7, v112
	v_exp_f32_e32 v8, v113
	v_exp_f32_e32 v9, v114
	v_exp_f32_e32 v10, v115
	v_exp_f32_e32 v11, v116
	v_add_f32_e32 v5, 0, v7
	v_exp_f32_e32 v12, v117
	v_add_f32_e32 v5, v8, v5
	v_exp_f32_e32 v13, v118
	v_add_f32_e32 v5, v9, v5
	v_exp_f32_e32 v14, v119
	v_add_f32_e32 v5, v10, v5
	v_exp_f32_e32 v15, v120
	v_add_f32_e32 v5, v11, v5
	v_exp_f32_e32 v96, v121
	v_add_f32_e32 v5, v12, v5
	v_exp_f32_e32 v97, v122
	v_add_f32_e32 v5, v13, v5
	v_exp_f32_e32 v98, v123
	v_add_f32_e32 v5, v14, v5
	v_exp_f32_e32 v99, v124
	v_add_f32_e32 v5, v15, v5
	v_exp_f32_e32 v100, v125
	v_add_f32_e32 v5, v96, v5
	v_exp_f32_e32 v101, v126
	v_add_f32_e32 v5, v97, v5
	v_exp_f32_e32 v102, v127
	v_add_f32_e32 v5, v98, v5
	v_exp_f32_e32 v80, v80
	v_add_f32_e32 v5, v99, v5
	v_exp_f32_e32 v81, v81
	v_add_f32_e32 v5, v100, v5
	v_exp_f32_e32 v82, v82
	v_add_f32_e32 v5, v101, v5
	v_exp_f32_e32 v83, v83
	v_add_f32_e32 v5, v102, v5
	v_exp_f32_e32 v84, v84
	v_add_f32_e32 v5, v80, v5
	v_exp_f32_e32 v85, v85
	v_add_f32_e32 v5, v81, v5
	v_exp_f32_e32 v86, v86
	v_add_f32_e32 v5, v82, v5
	v_exp_f32_e32 v87, v87
	v_add_f32_e32 v5, v83, v5
	v_exp_f32_e32 v88, v88
	v_add_f32_e32 v5, v84, v5
	v_exp_f32_e32 v89, v89
	v_add_f32_e32 v5, v85, v5
	v_exp_f32_e32 v90, v90
	v_add_f32_e32 v5, v86, v5
	v_exp_f32_e32 v91, v91
	v_add_f32_e32 v5, v87, v5
	v_exp_f32_e32 v92, v92
	v_add_f32_e32 v5, v88, v5
	v_exp_f32_e32 v93, v93
	v_add_f32_e32 v5, v89, v5
	v_exp_f32_e32 v94, v94
	v_add_f32_e32 v5, v90, v5
	v_exp_f32_e32 v95, v95
	v_add_f32_e32 v5, v91, v5
	v_add_f32_e32 v5, v92, v5
	v_add_f32_e32 v5, v93, v5
	v_add_f32_e32 v5, v94, v5
	v_add_f32_e32 v5, v95, v5
	v_mov_b32_e32 v6, v5
	s_nop 1
	v_permlane32_swap_b32_e32 v5, v6
	v_cvt_pk_bf16_f32 v8, v7, v8
	v_cvt_pk_bf16_f32 v9, v9, v10
	v_cvt_pk_bf16_f32 v10, v11, v12
	v_cvt_pk_bf16_f32 v11, v13, v14
	v_cvt_pk_bf16_f32 v12, v15, v96
	v_cvt_pk_bf16_f32 v13, v97, v98
	v_cvt_pk_bf16_f32 v14, v99, v100
	v_cvt_pk_bf16_f32 v15, v101, v102
	v_cvt_pk_bf16_f32 v80, v80, v81
	v_cvt_pk_bf16_f32 v81, v82, v83
	v_cvt_pk_bf16_f32 v82, v84, v85
	v_cvt_pk_bf16_f32 v83, v86, v87
	v_cvt_pk_bf16_f32 v84, v88, v89
	v_cvt_pk_bf16_f32 v85, v90, v91
	v_cvt_pk_bf16_f32 v86, v92, v93
	v_cvt_pk_bf16_f32 v87, v94, v95
	v_permlane32_swap_b32_e32 v8, v10
	v_permlane32_swap_b32_e32 v9, v11
	v_permlane32_swap_b32_e32 v12, v14
	v_permlane32_swap_b32_e32 v13, v15
	v_permlane32_swap_b32_e32 v80, v82
	v_permlane32_swap_b32_e32 v81, v83
	v_permlane32_swap_b32_e32 v84, v86
	v_permlane32_swap_b32_e32 v85, v87
	v_add_u32_e32 v7, s36, v175
	ds_read_b64_tr_b16 v[88:89], v7 offset:0
	ds_read_b64_tr_b16 v[90:91], v7 offset:0x800
	ds_read_b64_tr_b16 v[92:93], v7 offset:0x1000
	ds_read_b64_tr_b16 v[94:95], v7 offset:0x1800
	ds_read_b64_tr_b16 v[96:97], v7 offset:0x2000
	ds_read_b64_tr_b16 v[98:99], v7 offset:0x2800
	ds_read_b64_tr_b16 v[100:101], v7 offset:0x3000
	ds_read_b64_tr_b16 v[102:103], v7 offset:0x3800
	v_cmp_gt_u32_e32 vcc, 32, v169
	s_waitcnt lgkmcnt(0)
	s_nop 0
	v_mfma_f32_32x32x16_bf16 v[64:79], v[8:11], v[88:91], v[64:79]
	ds_read_b64_tr_b16 v[88:89], v7 offset:0x200
	ds_read_b64_tr_b16 v[90:91], v7 offset:0xa00
	ds_read_b64_tr_b16 v[104:105], v7 offset:0x1200
	ds_read_b64_tr_b16 v[106:107], v7 offset:0x1a00
	ds_read_b64_tr_b16 v[108:109], v7 offset:0x2200
	ds_read_b64_tr_b16 v[110:111], v7 offset:0x2a00
	ds_read_b64_tr_b16 v[112:113], v7 offset:0x3200
	v_mfma_f32_32x32x16_bf16 v[64:79], v[12:15], v[92:95], v[64:79]
	ds_read_b64_tr_b16 v[114:115], v7 offset:0x3a00
	s_nop 0
	s_waitcnt lgkmcnt(0)
	v_mfma_f32_32x32x16_bf16 v[64:79], v[80:83], v[96:99], v[64:79]
	v_mfma_f32_32x32x16_bf16 v[48:63], v[8:11], v[88:91], v[48:63]
	ds_read_b64_tr_b16 v[88:89], v7 offset:0x400
	ds_read_b64_tr_b16 v[90:91], v7 offset:0xc00
	ds_read_b64_tr_b16 v[92:93], v7 offset:0x1400
	ds_read_b64_tr_b16 v[94:95], v7 offset:0x1c00
	ds_read_b64_tr_b16 v[96:97], v7 offset:0x2400
	ds_read_b64_tr_b16 v[98:99], v7 offset:0x2c00
	v_mfma_f32_32x32x16_bf16 v[64:79], v[84:87], v[100:103], v[64:79]
	ds_read_b64_tr_b16 v[100:101], v7 offset:0x3400
	ds_read_b64_tr_b16 v[102:103], v7 offset:0x3c00
	s_nop 0
	s_waitcnt lgkmcnt(0)
	s_nop 0
	v_mfma_f32_32x32x16_bf16 v[32:47], v[8:11], v[88:91], v[32:47]
	ds_read_b64_tr_b16 v[88:89], v7 offset:0x600
	ds_read_b64_tr_b16 v[90:91], v7 offset:0xe00
	v_mfma_f32_32x32x16_bf16 v[32:47], v[12:15], v[92:95], v[32:47]
	ds_read_b64_tr_b16 v[92:93], v7 offset:0x1600
	ds_read_b64_tr_b16 v[94:95], v7 offset:0x1e00
	v_mfma_f32_32x32x16_bf16 v[32:47], v[80:83], v[96:99], v[32:47]
	ds_read_b64_tr_b16 v[96:97], v7 offset:0x2600
	ds_read_b64_tr_b16 v[98:99], v7 offset:0x2e00
	v_mfma_f32_32x32x16_bf16 v[32:47], v[84:87], v[100:103], v[32:47]
	ds_read_b64_tr_b16 v[100:101], v7 offset:0x3600
	ds_read_b64_tr_b16 v[102:103], v7 offset:0x3e00
	s_nop 0
	s_waitcnt lgkmcnt(0)
	s_nop 0
	v_mfma_f32_32x32x16_bf16 v[16:31], v[8:11], v[88:91], v[16:31]
	v_mfma_f32_32x32x16_bf16 v[48:63], v[12:15], v[104:107], v[48:63]
	v_mfma_f32_32x32x16_bf16 v[16:31], v[12:15], v[92:95], v[16:31]
	v_mfma_f32_32x32x16_bf16 v[48:63], v[80:83], v[108:111], v[48:63]
	v_mfma_f32_32x32x16_bf16 v[16:31], v[80:83], v[96:99], v[16:31]
	v_mfma_f32_32x32x16_bf16 v[48:63], v[84:87], v[112:115], v[48:63]
	v_mfma_f32_32x32x16_bf16 v[16:31], v[84:87], v[100:103], v[16:31]
	s_and_saveexec_b64 s[4:5], vcc
	v_add_f32_e32 v2, v2, v3
	v_fmac_f32_e32 v2, v177, v0
	v_add_f32_e32 v0, v5, v6
	v_fmac_f32_e32 v0, v2, v4
	ds_write_b32 v174, v0
	s_or_b64 exec, exec, s[4:5]
	s_waitcnt lgkmcnt(0)
	v_add_u32_e32 v0, s11, v176
	ds_read_b128 v[2:5], v0
	ds_read_b128 v[6:9], v0 offset:32
	s_lshl_b32 s4, s55, 14
	s_add_i32 s4, s4, 0
	s_cmp_lg_u32 s54, 1
	s_waitcnt lgkmcnt(1)
	v_rcp_f32_e32 v86, v2
	v_rcp_f32_e32 v87, v3
	v_rcp_f32_e32 v88, v4
	v_rcp_f32_e32 v89, v5
	s_waitcnt lgkmcnt(0)
	v_rcp_f32_e32 v90, v6
	ds_read_b128 v[2:5], v0 offset:64
	v_rcp_f32_e32 v83, v7
	v_rcp_f32_e32 v84, v8
	v_rcp_f32_e32 v85, v9
	ds_read_b128 v[6:9], v0 offset:96
	s_waitcnt lgkmcnt(1)
	v_rcp_f32_e32 v80, v2
	v_rcp_f32_e32 v81, v3
	v_rcp_f32_e32 v82, v4
	v_rcp_f32_e32 v10, v5
	s_waitcnt lgkmcnt(0)
	v_rcp_f32_e32 v11, v6
	v_rcp_f32_e32 v12, v7
	v_rcp_f32_e32 v13, v8
	v_rcp_f32_e32 v9, v9
	v_lshl_add_u32 v91, v169, 2, s4
	s_barrier
; template <int MODE>
; __device__ __forceinline__ void attn_unit(bf16r* P0, const bf16r* __restrict__ PKV, int rowbase, int seqL, int h, int blk, float lam,
;                                           const float* __restrict__ subg, const float* __restrict__ tsrc, char* lds) {
;     ...
;   if constexpr (MODE == 0) {
;     float* X = (float*)lds + (wid & 3) * 4096;
;     if (cmap == 1) {
; #pragma unroll
;       for (int d0 = 0; d0 < 4; ++d0)
; #pragma unroll
;         for (int r = 0; r < 16; ++r) X[(d0 * 16 + r) * 64 + lane] = o[d0][r] * rli[r] * lam;
;     }
	s_cbranch_scc1 .LBB0_244
	v_mul_f32_e32 v0, v64, v86
	v_mul_f32_e32 v2, v65, v87
	v_mul_f32_e32 v0, v170, v0
	v_mul_f32_e32 v2, v170, v2
	ds_write2st64_b32 v91, v0, v2 offset1:1
	v_mul_f32_e32 v0, v66, v88
	v_mul_f32_e32 v2, v67, v89
	v_mul_f32_e32 v0, v170, v0
	v_mul_f32_e32 v2, v170, v2
	ds_write2st64_b32 v91, v0, v2 offset0:2 offset1:3
	v_mul_f32_e32 v0, v68, v90
	v_mul_f32_e32 v2, v69, v83
	v_mul_f32_e32 v0, v170, v0
	v_mul_f32_e32 v2, v170, v2
	ds_write2st64_b32 v91, v0, v2 offset0:4 offset1:5
	v_mul_f32_e32 v0, v70, v84
	v_mul_f32_e32 v2, v71, v85
	v_mul_f32_e32 v0, v170, v0
	v_mul_f32_e32 v2, v170, v2
	ds_write2st64_b32 v91, v0, v2 offset0:6 offset1:7
	v_mul_f32_e32 v0, v72, v80
	v_mul_f32_e32 v2, v73, v81
	v_mul_f32_e32 v0, v170, v0
	v_mul_f32_e32 v2, v170, v2
	ds_write2st64_b32 v91, v0, v2 offset0:8 offset1:9
	v_mul_f32_e32 v0, v74, v82
	v_mul_f32_e32 v2, v75, v10
	v_mul_f32_e32 v0, v170, v0
	v_mul_f32_e32 v2, v170, v2
	ds_write2st64_b32 v91, v0, v2 offset0:10 offset1:11
	v_mul_f32_e32 v0, v76, v11
	v_mul_f32_e32 v2, v77, v12
	v_mul_f32_e32 v0, v170, v0
	v_mul_f32_e32 v2, v170, v2
	ds_write2st64_b32 v91, v0, v2 offset0:12 offset1:13
	v_mul_f32_e32 v0, v78, v13
	v_mul_f32_e32 v2, v79, v9
	v_mul_f32_e32 v0, v170, v0
	v_mul_f32_e32 v2, v170, v2
	ds_write2st64_b32 v91, v0, v2 offset0:14 offset1:15
	v_mul_f32_e32 v0, v48, v86
	v_mul_f32_e32 v2, v49, v87
	v_mul_f32_e32 v0, v170, v0
	v_mul_f32_e32 v2, v170, v2
	ds_write2st64_b32 v91, v0, v2 offset0:16 offset1:17
	v_mul_f32_e32 v0, v50, v88
	v_mul_f32_e32 v2, v51, v89
	v_mul_f32_e32 v0, v170, v0
	v_mul_f32_e32 v2, v170, v2
	ds_write2st64_b32 v91, v0, v2 offset0:18 offset1:19
	v_mul_f32_e32 v0, v52, v90
	v_mul_f32_e32 v2, v53, v83
	v_mul_f32_e32 v0, v170, v0
	v_mul_f32_e32 v2, v170, v2
	ds_write2st64_b32 v91, v0, v2 offset0:20 offset1:21
	v_mul_f32_e32 v0, v54, v84
	v_mul_f32_e32 v2, v55, v85
	v_mul_f32_e32 v0, v170, v0
	v_mul_f32_e32 v2, v170, v2
	ds_write2st64_b32 v91, v0, v2 offset0:22 offset1:23
	v_mul_f32_e32 v0, v56, v80
	v_mul_f32_e32 v2, v57, v81
	v_mul_f32_e32 v0, v170, v0
	v_mul_f32_e32 v2, v170, v2
	ds_write2st64_b32 v91, v0, v2 offset0:24 offset1:25
	v_mul_f32_e32 v0, v58, v82
	v_mul_f32_e32 v2, v59, v10
	v_mul_f32_e32 v0, v170, v0
	v_mul_f32_e32 v2, v170, v2
	ds_write2st64_b32 v91, v0, v2 offset0:26 offset1:27
	v_mul_f32_e32 v0, v60, v11
	v_mul_f32_e32 v2, v61, v12
	v_mul_f32_e32 v0, v170, v0
	v_mul_f32_e32 v2, v170, v2
	ds_write2st64_b32 v91, v0, v2 offset0:28 offset1:29
	v_mul_f32_e32 v0, v62, v13
	v_mul_f32_e32 v2, v63, v9
	v_mul_f32_e32 v0, v170, v0
	v_mul_f32_e32 v2, v170, v2
	ds_write2st64_b32 v91, v0, v2 offset0:30 offset1:31
	v_mul_f32_e32 v0, v32, v86
	v_mul_f32_e32 v2, v33, v87
	v_mul_f32_e32 v0, v170, v0
	v_mul_f32_e32 v2, v170, v2
	ds_write2st64_b32 v91, v0, v2 offset0:32 offset1:33
	v_mul_f32_e32 v0, v34, v88
	v_mul_f32_e32 v2, v35, v89
	v_mul_f32_e32 v0, v170, v0
	v_mul_f32_e32 v2, v170, v2
	ds_write2st64_b32 v91, v0, v2 offset0:34 offset1:35
	v_mul_f32_e32 v0, v36, v90
	v_mul_f32_e32 v2, v37, v83
	v_mul_f32_e32 v0, v170, v0
	v_mul_f32_e32 v2, v170, v2
	ds_write2st64_b32 v91, v0, v2 offset0:36 offset1:37
	v_mul_f32_e32 v0, v38, v84
	v_mul_f32_e32 v2, v39, v85
	v_mul_f32_e32 v0, v170, v0
	v_mul_f32_e32 v2, v170, v2
	ds_write2st64_b32 v91, v0, v2 offset0:38 offset1:39
	v_mul_f32_e32 v0, v40, v80
	v_mul_f32_e32 v2, v41, v81
	v_mul_f32_e32 v0, v170, v0
	v_mul_f32_e32 v2, v170, v2
	ds_write2st64_b32 v91, v0, v2 offset0:40 offset1:41
	v_mul_f32_e32 v0, v42, v82
	v_mul_f32_e32 v2, v43, v10
	v_mul_f32_e32 v0, v170, v0
	v_mul_f32_e32 v2, v170, v2
	ds_write2st64_b32 v91, v0, v2 offset0:42 offset1:43
	v_mul_f32_e32 v0, v44, v11
	v_mul_f32_e32 v2, v45, v12
	v_mul_f32_e32 v0, v170, v0
	v_mul_f32_e32 v2, v170, v2
	ds_write2st64_b32 v91, v0, v2 offset0:44 offset1:45
	v_mul_f32_e32 v0, v46, v13
	v_mul_f32_e32 v2, v47, v9
	v_mul_f32_e32 v0, v170, v0
	v_mul_f32_e32 v2, v170, v2
	ds_write2st64_b32 v91, v0, v2 offset0:46 offset1:47
	v_mul_f32_e32 v0, v16, v86
	v_mul_f32_e32 v2, v17, v87
	v_mul_f32_e32 v0, v170, v0
	v_mul_f32_e32 v2, v170, v2
	ds_write2st64_b32 v91, v0, v2 offset0:48 offset1:49
	v_mul_f32_e32 v0, v18, v88
	v_mul_f32_e32 v2, v19, v89
	v_mul_f32_e32 v0, v170, v0
	v_mul_f32_e32 v2, v170, v2
	ds_write2st64_b32 v91, v0, v2 offset0:50 offset1:51
	v_mul_f32_e32 v0, v20, v90
	v_mul_f32_e32 v2, v21, v83
	v_mul_f32_e32 v0, v170, v0
	v_mul_f32_e32 v2, v170, v2
	ds_write2st64_b32 v91, v0, v2 offset0:52 offset1:53
	v_mul_f32_e32 v0, v22, v84
	v_mul_f32_e32 v2, v23, v85
	v_mul_f32_e32 v0, v170, v0
	v_mul_f32_e32 v2, v170, v2
	ds_write2st64_b32 v91, v0, v2 offset0:54 offset1:55
	v_mul_f32_e32 v0, v24, v80
	v_mul_f32_e32 v2, v25, v81
	v_mul_f32_e32 v0, v170, v0
	v_mul_f32_e32 v2, v170, v2
	ds_write2st64_b32 v91, v0, v2 offset0:56 offset1:57
	v_mul_f32_e32 v0, v26, v82
	v_mul_f32_e32 v2, v27, v10
	v_mul_f32_e32 v0, v170, v0
	v_mul_f32_e32 v2, v170, v2
	ds_write2st64_b32 v91, v0, v2 offset0:58 offset1:59
	v_mul_f32_e32 v0, v28, v11
	v_mul_f32_e32 v2, v29, v12
	v_mul_f32_e32 v0, v170, v0
	v_mul_f32_e32 v2, v170, v2
	ds_write2st64_b32 v91, v0, v2 offset0:60 offset1:61
	v_mul_f32_e32 v0, v30, v13
	v_mul_f32_e32 v2, v31, v9
	v_mul_f32_e32 v0, v170, v0
	v_mul_f32_e32 v2, v170, v2
	ds_write2st64_b32 v91, v0, v2 offset0:62 offset1:63
